# remap + SSD sample chains at s_setprio 0 (DN chain partner yields VALU issue)
# baseline (speedup 1.0000x reference)
.LBB0_640:
	s_or_b64 exec, exec, s[44:45]
	s_andn2_b64 vcc, exec, s[34:35]
	s_cbranch_vccnz .LBB0_642
	s_setprio 0
